# grid barrier between P4 (attention part 2 + sample out-proj) and P5 (HGRN pass 3) removed: the two phases touch disjoint data, so they run as one phase
# speedup vs baseline: 1.0038x; 1.0038x over previous
; __device__ __forceinline__ unsigned xb_ld(unsigned* p)              { return __hip_atomic_load(p, __ATOMIC_RELAXED, __HIP_MEMORY_SCOPE_AGENT); }
; __device__ __forceinline__ unsigned xb_add(unsigned* p, unsigned v) { return __hip_atomic_fetch_add(p, v, __ATOMIC_RELAXED, __HIP_MEMORY_SCOPE_AGENT); }
; #define XB_SPIN(cond, bar) do { unsigned _sp = 0; while (cond) { __builtin_amdgcn_s_sleep(1); \
;     if ((++_sp & 255u) == 0u) { if (xb_ld(&(bar)[XB_TMO])) break; if (_sp > XB_SPIN_CAP) { atomicAdd(&(bar)[XB_TMO], 1u); break; } } } } while (0)
; #define SEAM(k) do { if (IN(k) && IN((k) + 1)) { if (P.ph_lo < 0) grid.sync(); else xcd_barrier(xbar); } } while (0)
; __device__ __forceinline__ void xcd_barrier(const XcdBarrier& b) {
;     asm volatile("s_waitcnt vmcnt(0)" ::: "memory");
;     __syncthreads();
;     if (threadIdx.x == 0) {
;         unsigned* bar = b.bar;
;         __builtin_amdgcn_s_waitcnt(0);
;         unsigned nloc = b.st[0], nx = b.st[1];
;         if (nloc == 0u) { xcd_barrier_complete(bar, b.x, nloc, nx); b.st[0] = nloc; b.st[1] = nx; }
;         const unsigned old = xb_add(&bar[XB_XSUB(b.x)], 1u);
;         const unsigned gen = old / nloc;
;         if (old + 1u == (gen + 1u) * nloc) {
;             __builtin_amdgcn_fence(__ATOMIC_RELEASE, "agent");
;             asm volatile("s_waitcnt vmcnt(0)" ::: "memory");
;             const unsigned og = xb_add(&bar[XB_TOP], 1u);
;             const unsigned tg = og / nx;
;             if (og + 1u == (tg + 1u) * nx) xb_add(&bar[XB_TOPGEN], 1u);
;             else XB_SPIN(xb_ld(&bar[XB_TOPGEN]) == tg, bar);
;             __builtin_amdgcn_fence(__ATOMIC_ACQUIRE, "agent");
;             xb_add(&bar[XB_XGEN(b.x)], 1u);
;             asm volatile("s_waitcnt vmcnt(0)" ::: "memory");
;         } else {
;             XB_SPIN(xb_ld(&bar[XB_XGEN(b.x)]) == gen, bar);
;             __builtin_amdgcn_fence(__ATOMIC_ACQUIRE, "agent");
;             asm volatile("s_waitcnt vmcnt(0)" ::: "memory");
;         }
;     }
;     __syncthreads();
; }
; __global__ void __launch_bounds__(512, 2) fwd_kernel(Params P) {
;     ...
;     SEAM(4);
.LBB0_1097:
	s_cmp_gt_i32 s91, 5
	s_cselect_b64 s[4:5], -1, 0
	s_and_b64 s[6:7], s[52:53], s[4:5]
	s_branch .LBB0_1165
